# grid barrier: XCD leader no longer waits for its release atomic to be acknowledged before leaving the barrier
# speedup vs baseline: 1.0132x; 1.0074x over previous
.LBB0_96:
	s_or_b64 exec, exec, s[4:5]
.LBB0_97:
	s_or_b64 exec, exec, s[6:7]
	s_add_u32 s38, s26, 0x7200000
	s_addc_u32 s39, s27, 0
	s_add_u32 s20, s26, 0x800000
	s_addc_u32 s21, s27, 0
	v_mov_b32_e32 v85, v254
	s_waitcnt lgkmcnt(0)
	s_barrier
	s_add_u32 s18, s26, 0x2300000
	s_addc_u32 s19, s27, 0
	v_readfirstlane_b32 s0, v85
	s_ashr_i32 s23, s0, 6
	v_writelane_b32 v255, s58, 10
	s_cmp_lt_i32 s23, 4
	s_mov_b64 s[0:1], -1
	v_writelane_b32 v255, s59, 11
	s_cbranch_scc0 .LBB0_174
	s_add_u32 s40, s26, 0x2000
	s_addc_u32 s41, s27, 0
	s_add_u32 s42, s26, 0xc000
	s_addc_u32 s43, s27, 0
	s_add_u32 s44, s26, 0xe000
	s_addc_u32 s45, s27, 0
	s_cmpk_lt_i32 s2, 0x2100
	s_cselect_b64 s[0:1], -1, 0
	s_add_u32 s46, s26, 0x40000
	s_addc_u32 s47, s27, 0
	s_add_u32 s48, s26, 0x9300000
	s_addc_u32 s49, s27, 0
	s_add_u32 s50, s26, 0xb400000
	s_addc_u32 s51, s27, 0
	s_add_u32 s52, s26, 0xd500000
	s_addc_u32 s53, s27, 0
	s_add_u32 s54, s26, 0xf600000
	s_addc_u32 s55, s27, 0
	s_add_u32 s56, s26, 0x11700000
	s_mov_b64 s[4:5], s[58:59]
	v_cndmask_b32_e64 v0, 0, 1, s[0:1]
	s_brev_b32 s60, 63
	v_lshlrev_b32_e32 v87, 2, v85
	s_addc_u32 s57, s27, 0
	s_lshl_b32 s24, s30, 1
	s_mov_b32 s8, 0
	s_mov_b64 s[58:59], -1
	v_mov_b64_e32 v[68:69], s[4:5]
	v_cmp_ne_u32_e64 s[6:7], 1, v0
	v_mov_b32_e32 v89, 0
	s_mov_b32 s61, -1
	s_branch .LBB0_100

.LBB0_294:
	s_or_b64 exec, exec, s[4:5]
.LBB0_295:
	s_or_b64 exec, exec, s[10:11]

.LBB0_525:
	s_or_b64 exec, exec, s[4:5]
.LBB0_526:
	s_or_b64 exec, exec, s[10:11]

.LBB0_598:
	s_or_b64 exec, exec, s[4:5]
.LBB0_599:
	s_or_b64 exec, exec, s[10:11]

.LBB0_783:
	s_or_b64 exec, exec, s[4:5]
.LBB0_784:
	s_or_b64 exec, exec, s[6:7]
	v_readlane_b32 s0, v255, 10
	v_readlane_b32 s1, v255, 11
	s_waitcnt lgkmcnt(0)
	v_mov_b32_e32 v0, v254
	s_waitcnt vmcnt(0)
	v_mov_b64_e32 v[2:3], s[0:1]
	s_barrier
	flat_load_dwordx2 v[4:5], v[2:3] offset:200 sc0 sc1
	flat_load_dwordx2 v[6:7], v[2:3] offset:208 sc0 sc1
	flat_load_dwordx2 v[8:9], v[2:3] offset:216 sc0 sc1
	flat_load_dwordx2 v[2:3], v[2:3] offset:224 sc0 sc1
	s_waitcnt vmcnt(0)
	s_add_u32 s8, s26, 0xf200000
	v_readfirstlane_b32 s0, v0
	s_addc_u32 s9, s27, 0
	s_ashr_i32 s0, s0, 6
	v_readlane_b32 s1, v255, 6
	s_add_i32 s20, s0, s1
	s_cmp_lt_i32 s20, 0x10000
	s_waitcnt lgkmcnt(0)
	v_readfirstlane_b32 s11, v5
	v_readfirstlane_b32 s10, v4
	v_readfirstlane_b32 s13, v7
	v_readfirstlane_b32 s12, v6
	v_readfirstlane_b32 s15, v9
	v_readfirstlane_b32 s14, v8
	v_readfirstlane_b32 s17, v3
	v_readfirstlane_b32 s16, v2
	s_cbranch_scc0 .LBB0_787
	s_add_u32 s18, s26, 0xb200000
	s_addc_u32 s19, s27, 0
	v_lshlrev_b32_e32 v0, 2, v0
	s_lshl_b32 s1, s2, 11
	s_lshl_b32 s0, s0, 8
	v_and_b32_e32 v2, 0xfc, v0
	s_add_i32 s21, s1, s0
	s_lshl_b32 s23, s30, 11
	v_mov_b32_e32 v3, 0x3a27c5ac
	s_mov_b32 s24, 0xf800000
	v_mov_b32_e32 v4, 0x260
	v_mov_b32_e32 v1, 0
	s_movk_i32 s25, 0x1000

.LBB0_838:
	s_or_b64 exec, exec, s[4:5]
.LBB0_839:
	s_or_b64 exec, exec, s[6:7]
	s_waitcnt lgkmcnt(0)
	v_mov_b32_e32 v0, v254
	v_readlane_b32 s0, v255, 10
	s_barrier
	v_readlane_b32 s1, v255, 11
	v_mov_b32_e32 v8, v254
	s_nop 0
	v_mov_b64_e32 v[0:1], s[0:1]
	flat_load_dwordx2 v[0:1], v[0:1] sc0 sc1
	s_waitcnt vmcnt(0)
	v_readlane_b32 s0, v255, 7
	v_readlane_b32 s1, v255, 8
	s_and_b64 vcc, exec, s[0:1]
	s_waitcnt lgkmcnt(0)
	v_readfirstlane_b32 s11, v1
	v_readfirstlane_b32 s20, v8
	v_readfirstlane_b32 s10, v0
	s_cbranch_vccz .LBB0_855
	v_lshlrev_b32_e32 v0, 4, v8
	v_add_u32_e32 v1, 0x2000, v0
	v_ashrrev_i32_e32 v2, 31, v1
	v_lshrrev_b32_e32 v2, 22, v2
	v_add_u32_e32 v2, v1, v2
	v_ashrrev_i32_e32 v9, 10, v2
	v_mul_i32_i24_e32 v2, 0x400, v9
	v_sub_u32_e32 v1, v1, v2
	v_lshrrev_b32_e32 v2, 4, v1
	v_bitop3_b32 v1, v2, v1, 32 bitop3:0x6c
	v_ashrrev_i32_e32 v2, 31, v1
	s_lshr_b32 s4, s3, 29
	v_lshrrev_b32_e32 v2, 26, v2
	s_add_i32 s4, s2, s4
	v_add_u32_e32 v2, v1, v2
	s_and_b32 s5, s4, -8
	s_ashr_i32 s1, s20, 6
	v_ashrrev_i32_e32 v10, 6, v2
	v_and_b32_e32 v2, 0xc0, v2
	s_sub_i32 s5, s2, s5
	s_ashr_i32 s0, s20, 8
	s_lshl_b32 s21, s1, 10
	v_sub_u32_e32 v1, v1, v2
	v_mov_b32_e32 v2, 1
	s_lshl_b32 s7, s5, 5
	s_ashr_i32 s4, s4, 3
	v_ashrrev_i16_sdwa v1, v2, sext(v1) dst_sel:DWORD dst_unused:UNUSED_PAD src0_sel:DWORD src1_sel:BYTE_0
	s_mul_i32 s6, s5, 33
	s_cmp_lt_i32 s5, 0
	v_bfe_i32 v12, v1, 0, 16
	v_bfe_i32 v1, v8, 27, 1
	s_cselect_b32 s5, s6, s7
	v_lshrrev_b32_e32 v1, 22, v1
	s_add_i32 s4, s5, s4
	v_add_u32_e32 v1, v0, v1
	s_ashr_i32 s5, s4, 31
	v_and_b32_e32 v1, 0xfffffc00, v1
	s_lshr_b32 s5, s5, 26
	v_sub_u32_e32 v0, v0, v1
	s_add_i32 s5, s4, s5
	v_lshrrev_b32_e32 v1, 4, v0
	s_ashr_i32 s6, s5, 6
	s_andn2_b32 s5, s5, 63
	v_bitop3_b32 v1, v1, v0, 32 bitop3:0x6c
	v_ashrrev_i32_e32 v0, 31, v0
	s_sub_i32 s5, s4, s5
	v_lshrrev_b32_e32 v0, 26, v0
	s_bfe_i32 s4, s5, 0x80000
	v_add_u32_e32 v0, v1, v0
	s_bfe_u32 s4, s4, 0x3000c
	v_lshlrev_b32_e32 v3, 3, v9
	v_ashrrev_i32_e32 v13, 6, v0
	v_ashrrev_i32_e32 v0, 31, v8
	s_add_i32 s7, s5, s4
	v_and_b32_e32 v3, 0xffff0, v3
	v_lshlrev_b32_e32 v4, 5, v9
	v_lshrrev_b32_e32 v0, 26, v0
	s_bfe_i32 s4, s7, 0x80000
	s_and_b32 s7, s7, 0xf8
	v_add_u32_e32 v3, v10, v3
	v_and_b32_e32 v11, 32, v4
	v_add_u32_e32 v0, v8, v0
	s_sub_i32 s5, s5, s7
	v_lshl_or_b32 v3, v3, 11, v11
	v_ashrrev_i32_e32 v14, 6, v0
	s_lshl_b32 s6, s6, 3
	s_sext_i32_i16 s4, s4
	s_sext_i32_i8 s5, s5
	v_add_lshl_u32 v128, v3, v12, 1
	v_lshlrev_b32_e32 v3, 5, v14
	s_lshr_b32 s4, s4, 3
	s_add_i32 s72, s6, s5
	v_lshlrev_b32_e32 v0, 3, v14
	v_and_b32_e32 v15, 32, v3
	v_mul_i32_i24_e32 v3, 64, v13
	s_ashr_i32 s73, s72, 31
	s_bfe_i64 s[12:13], s[4:5], 0x100000
	v_and_b32_e32 v0, 0xffff0, v0
	v_sub_u32_e32 v1, v1, v3
	s_lshl_b64 s[6:7], s[72:73], 20
	s_lshl_b64 s[12:13], s[12:13], 20
	v_add_u32_e32 v0, v13, v0
	v_ashrrev_i16_sdwa v1, v2, sext(v1) dst_sel:DWORD dst_unused:UNUSED_PAD src0_sel:DWORD src1_sel:BYTE_0
	s_add_u32 s50, s64, s12
	v_lshl_or_b32 v0, v0, 11, v15
	v_bfe_i32 v16, v1, 0, 16
	s_addc_u32 s51, s65, s13
	s_add_i32 s23, s21, 0
	v_add_lshl_u32 v130, v0, v16, 1
	s_add_i32 m0, s23, 0x10000
	s_load_dwordx2 s[12:13], s[88:89], 0x168
	global_load_lds_dwordx4 v130, s[50:51]
	s_add_i32 m0, s23, 0x12000
	s_add_u32 s74, s8, s6
	global_load_lds_dwordx4 v128, s[50:51]
	s_addc_u32 s75, s9, s7
	s_mov_b32 m0, s23
	s_add_i32 s24, s23, 0x2000
	global_load_lds_dwordx4 v130, s[74:75]
	s_mov_b32 m0, s24
	s_add_u32 s6, s50, 0x80000
	global_load_lds_dwordx4 v128, s[74:75]
	s_addc_u32 s7, s51, 0
	s_add_i32 m0, s23, 0x14000
	v_mov_b32_e32 v131, 0
	global_load_lds_dwordx4 v130, s[6:7]
	s_add_i32 m0, s23, 0x16000
	v_mov_b32_e32 v129, v131
	global_load_lds_dwordx4 v128, s[6:7]
	s_add_u32 s6, s74, 0x80000
	s_addc_u32 s7, s75, 0
	s_add_i32 s25, s23, 0x4000
	s_mov_b32 m0, s25
	s_add_i32 s28, s23, 0x6000
	global_load_lds_dwordx4 v130, s[6:7]
	s_mov_b32 m0, s28
	s_mov_b32 s29, 0
	global_load_lds_dwordx4 v128, s[6:7]
	v_lshl_add_u64 v[6:7], s[50:51], 0, v[130:131]
	v_lshl_add_u64 v[4:5], s[50:51], 0, v[128:129]
	v_lshl_add_u64 v[2:3], s[74:75], 0, v[130:131]
	s_cmp_lg_u32 s0, 1
	v_lshl_add_u64 v[0:1], s[74:75], 0, v[128:129]
	s_cbranch_scc1 .LBB0_842
	s_barrier

.LBB0_906:
	s_or_b64 exec, exec, s[4:5]
.LBB0_907:
	s_or_b64 exec, exec, s[10:11]

.LBB0_978:
	s_or_b64 exec, exec, s[4:5]
.LBB0_979:
	s_or_b64 exec, exec, s[6:7]
	s_add_u32 s48, s26, 0x13200000
	s_addc_u32 s49, s27, 0
	s_cmpk_lt_i32 s2, 0x580
	s_cselect_b64 s[56:57], -1, 0
	v_mov_b32_e32 v128, v254
	v_mov_b32_e32 v9, v254
	s_waitcnt lgkmcnt(0)
	s_barrier
	s_and_b64 vcc, exec, s[56:57]
	v_readfirstlane_b32 s20, v9
	s_cbranch_vccz .LBB0_991
	v_lshlrev_b32_e32 v0, 4, v9
	v_add_u32_e32 v1, 0x2000, v0
	v_ashrrev_i32_e32 v2, 31, v1
	v_lshrrev_b32_e32 v2, 22, v2
	v_add_u32_e32 v2, v1, v2
	v_ashrrev_i32_e32 v8, 10, v2
	v_mul_i32_i24_e32 v2, 0x400, v8
	v_sub_u32_e32 v1, v1, v2
	v_lshrrev_b32_e32 v2, 4, v1
	v_bitop3_b32 v1, v2, v1, 32 bitop3:0x6c
	v_ashrrev_i32_e32 v2, 31, v1
	v_lshrrev_b32_e32 v2, 26, v2
	v_add_u32_e32 v2, v1, v2
	v_lshlrev_b32_e32 v3, 3, v8
	v_ashrrev_i32_e32 v10, 6, v2
	v_and_b32_e32 v3, -16, v3
	v_add_u32_e32 v3, v10, v3
	v_and_b32_e32 v4, 3, v10
	s_mov_b32 s4, 0xfffe0
	v_lshrrev_b32_e32 v5, 2, v3
	v_lshlrev_b32_e32 v6, 1, v3
	v_and_b32_e32 v2, 0xc0, v2
	v_and_or_b32 v4, v3, s4, v4
	v_and_b32_e32 v5, 4, v5
	v_and_b32_e32 v6, 24, v6
	v_sub_u32_e32 v1, v1, v2
	v_mov_b32_e32 v2, 1
	v_or3_b32 v4, v4, v5, v6
	v_lshlrev_b32_e32 v5, 5, v8
	v_ashrrev_i16_sdwa v1, v2, sext(v1) dst_sel:DWORD dst_unused:UNUSED_PAD src0_sel:DWORD src1_sel:BYTE_0
	v_and_b32_e32 v5, 32, v5
	v_bfe_i32 v11, v1, 0, 16
	v_add_lshl_u32 v1, v5, v11, 1
	v_lshl_add_u32 v130, v4, 12, v1
	v_lshl_add_u32 v132, v3, 12, v1
	v_bfe_i32 v1, v9, 27, 1
	v_lshrrev_b32_e32 v1, 22, v1
	v_add_u32_e32 v1, v0, v1
	v_and_b32_e32 v1, 0xfffffc00, v1
	v_sub_u32_e32 v0, v0, v1
	v_lshrrev_b32_e32 v1, 4, v0
	v_bitop3_b32 v1, v1, v0, 32 bitop3:0x6c
	v_ashrrev_i32_e32 v0, 31, v0
	v_lshrrev_b32_e32 v0, 26, v0
	v_add_u32_e32 v0, v1, v0
	v_ashrrev_i32_e32 v12, 6, v0
	v_ashrrev_i32_e32 v0, 31, v9
	v_lshrrev_b32_e32 v0, 26, v0
	v_add_u32_e32 v0, v9, v0
	v_ashrrev_i32_e32 v13, 6, v0
	v_lshlrev_b32_e32 v0, 3, v13
	v_and_b32_e32 v0, -16, v0
	v_add_u32_e32 v0, v12, v0
	v_and_b32_e32 v3, 3, v12
	v_and_or_b32 v3, v0, s4, v3
	s_lshr_b32 s4, s3, 29
	s_add_i32 s4, s2, s4
	s_ashr_i32 s1, s20, 6
	s_ashr_i32 s5, s4, 3
	s_and_b32 s4, s4, -8
	s_ashr_i32 s0, s20, 8
	s_lshl_b32 s21, s1, 10
	s_sub_i32 s4, s2, s4
	s_cmp_lt_i32 s4, 0
	s_movk_i32 s23, 0xb1
	s_cselect_b32 s6, s23, 0xb0
	s_mul_i32 s4, s4, s6
	s_add_i32 s4, s4, s5
	s_mul_hi_i32 s5, s4, 0x2e8ba2e9
	s_lshr_b32 s6, s5, 31
	s_ashr_i32 s5, s5, 6
	s_add_i32 s5, s5, s6
	s_lshl_b32 s6, s5, 3
	s_mulk_i32 s5, 0x160
	s_sub_i32 s5, s4, s5
	s_sext_i32_i16 s4, s5
	s_bfe_u32 s4, s4, 0x3001c
	s_add_i32 s7, s5, s4
	s_sext_i32_i16 s4, s7
	s_and_b32 s7, s7, 0xfff8
	v_lshrrev_b32_e32 v4, 2, v0
	v_lshlrev_b32_e32 v5, 1, v0
	s_sub_i32 s5, s5, s7
	v_and_b32_e32 v4, 4, v4
	v_and_b32_e32 v5, 24, v5
	s_sext_i32_i16 s5, s5
	v_or3_b32 v3, v3, v4, v5
	v_mul_i32_i24_e32 v5, 64, v12
	s_lshr_b32 s4, s4, 3
	s_add_i32 s18, s6, s5
	v_sub_u32_e32 v1, v1, v5
	s_ashr_i32 s19, s18, 31
	s_bfe_i64 s[8:9], s[4:5], 0x100000
	v_lshlrev_b32_e32 v4, 5, v13
	v_ashrrev_i16_sdwa v1, v2, sext(v1) dst_sel:DWORD dst_unused:UNUSED_PAD src0_sel:DWORD src1_sel:BYTE_0
	s_lshl_b64 s[6:7], s[18:19], 20
	s_lshl_b64 s[8:9], s[8:9], 20
	v_and_b32_e32 v4, 32, v4
	v_bfe_i32 v14, v1, 0, 16
	s_add_u32 s50, s62, s8
	v_add_lshl_u32 v1, v4, v14, 1
	s_addc_u32 s51, s63, s9
	s_add_i32 s19, s21, 0
	v_lshl_add_u32 v134, v3, 12, v1
	s_add_i32 m0, s19, 0x10000
	v_lshl_add_u32 v136, v0, 12, v1
	global_load_lds_dwordx4 v134, s[50:51]
	s_add_i32 m0, s19, 0x12000
	s_add_u32 s36, s38, s6
	global_load_lds_dwordx4 v130, s[50:51]
	s_addc_u32 s37, s39, s7
	s_mov_b32 m0, s19
	s_add_i32 s24, s19, 0x2000
	global_load_lds_dwordx4 v136, s[36:37]
	s_mov_b32 m0, s24
	s_add_u32 s6, s50, 0x80000
	global_load_lds_dwordx4 v132, s[36:37]
	s_addc_u32 s7, s51, 0
	s_add_i32 m0, s19, 0x14000
	v_mov_b32_e32 v135, 0
	global_load_lds_dwordx4 v134, s[6:7]
	s_add_i32 m0, s19, 0x16000
	v_mov_b32_e32 v131, v135
	global_load_lds_dwordx4 v130, s[6:7]
	s_add_u32 s6, s36, 0x80000
	s_addc_u32 s7, s37, 0
	s_add_i32 s25, s19, 0x4000
	s_mov_b32 m0, s25
	s_add_i32 s28, s19, 0x6000
	global_load_lds_dwordx4 v136, s[6:7]
	s_mov_b32 m0, s28
	v_mov_b32_e32 v137, v135
	global_load_lds_dwordx4 v132, s[6:7]
	v_mov_b32_e32 v133, v135
	s_mov_b32 s29, 0
	v_lshl_add_u64 v[6:7], s[50:51], 0, v[134:135]
	v_lshl_add_u64 v[4:5], s[50:51], 0, v[130:131]
	v_lshl_add_u64 v[2:3], s[36:37], 0, v[136:137]
	s_cmp_lg_u32 s0, 1
	v_lshl_add_u64 v[0:1], s[36:37], 0, v[132:133]
	s_cbranch_scc1 .LBB0_982
	s_barrier

.LBB0_1081:
	s_or_b64 exec, exec, s[4:5]
.LBB0_1082:
	s_or_b64 exec, exec, s[10:11]

.LBB0_1154:
	s_or_b64 exec, exec, s[4:5]
.LBB0_1155:
	s_or_b64 exec, exec, s[10:11]

.LBB0_1226:
	s_or_b64 exec, exec, s[4:5]
.LBB0_1227:
	s_or_b64 exec, exec, s[6:7]
	s_waitcnt lgkmcnt(0)
	v_mov_b32_e32 v0, v254
	s_barrier
	v_mov_b32_e32 v9, v254
	v_mov_b64_e32 v[0:1], s[40:41]
	flat_load_dwordx2 v[0:1], v[0:1] offset:240 sc0 sc1
	s_waitcnt vmcnt(0)
	s_cmpk_lt_i32 s2, 0x300
	s_waitcnt lgkmcnt(0)
	v_readfirstlane_b32 s9, v1
	v_readfirstlane_b32 s8, v0
	v_readfirstlane_b32 s23, v9
	s_cbranch_scc0 .LBB0_1239
	v_lshlrev_b32_e32 v0, 4, v9
	v_add_u32_e32 v1, 0x2000, v0
	v_ashrrev_i32_e32 v2, 31, v1
	v_lshrrev_b32_e32 v2, 22, v2
	v_add_u32_e32 v2, v1, v2
	v_ashrrev_i32_e32 v8, 10, v2
	v_mul_i32_i24_e32 v2, 0x400, v8
	v_sub_u32_e32 v1, v1, v2
	v_lshrrev_b32_e32 v2, 4, v1
	v_bitop3_b32 v1, v2, v1, 32 bitop3:0x6c
	v_ashrrev_i32_e32 v2, 31, v1
	v_lshrrev_b32_e32 v2, 26, v2
	v_add_u32_e32 v2, v1, v2
	v_lshlrev_b32_e32 v3, 3, v8
	v_ashrrev_i32_e32 v10, 6, v2
	v_and_b32_e32 v3, -16, v3
	v_add_u32_e32 v3, v10, v3
	v_and_b32_e32 v4, 3, v10
	s_mov_b32 s4, 0xfffe0
	v_lshrrev_b32_e32 v5, 2, v3
	v_lshlrev_b32_e32 v6, 1, v3
	v_and_b32_e32 v2, 0xc0, v2
	v_and_or_b32 v4, v3, s4, v4
	v_and_b32_e32 v5, 4, v5
	v_and_b32_e32 v6, 24, v6
	v_sub_u32_e32 v1, v1, v2
	v_mov_b32_e32 v2, 1
	v_or3_b32 v4, v4, v5, v6
	v_lshlrev_b32_e32 v5, 5, v8
	v_ashrrev_i16_sdwa v1, v2, sext(v1) dst_sel:DWORD dst_unused:UNUSED_PAD src0_sel:DWORD src1_sel:BYTE_0
	v_and_b32_e32 v5, 32, v5
	v_bfe_i32 v11, v1, 0, 16
	v_add_lshl_u32 v1, v5, v11, 1
	v_lshl_add_u32 v136, v4, 12, v1
	v_lshl_add_u32 v138, v3, 12, v1
	v_bfe_i32 v1, v9, 27, 1
	v_lshrrev_b32_e32 v1, 22, v1
	v_add_u32_e32 v1, v0, v1
	v_and_b32_e32 v1, 0xfffffc00, v1
	v_sub_u32_e32 v0, v0, v1
	v_lshrrev_b32_e32 v1, 4, v0
	v_bitop3_b32 v1, v1, v0, 32 bitop3:0x6c
	v_ashrrev_i32_e32 v0, 31, v0
	v_lshrrev_b32_e32 v0, 26, v0
	v_add_u32_e32 v0, v1, v0
	v_ashrrev_i32_e32 v12, 6, v0
	v_ashrrev_i32_e32 v0, 31, v9
	v_lshrrev_b32_e32 v0, 26, v0
	v_add_u32_e32 v0, v9, v0
	v_ashrrev_i32_e32 v13, 6, v0
	v_lshlrev_b32_e32 v0, 3, v13
	v_and_b32_e32 v0, -16, v0
	v_add_u32_e32 v0, v12, v0
	v_and_b32_e32 v3, 3, v12
	v_and_or_b32 v3, v0, s4, v3
	s_lshr_b32 s4, s3, 29
	s_add_i32 s4, s2, s4
	s_ashr_i32 s1, s23, 6
	s_ashr_i32 s5, s4, 3
	s_and_b32 s4, s4, -8
	s_ashr_i32 s0, s23, 8
	s_lshl_b32 s24, s1, 10
	s_sub_i32 s4, s2, s4
	s_cmp_lt_i32 s4, 0
	s_movk_i32 s25, 0x61
	s_cselect_b32 s6, s25, 0x60
	s_mul_i32 s4, s4, s6
	s_add_i32 s4, s4, s5
	s_mul_hi_i32 s5, s4, 0x2aaaaaab
	s_lshr_b32 s6, s5, 31
	s_ashr_i32 s5, s5, 5
	s_add_i32 s5, s5, s6
	s_lshl_b32 s6, s5, 3
	s_mulk_i32 s5, 0xc0
	s_sub_i32 s5, s4, s5
	s_sext_i32_i16 s4, s5
	s_bfe_u32 s4, s4, 0x3001c
	s_add_i32 s7, s5, s4
	s_sext_i32_i16 s4, s7
	s_and_b32 s7, s7, 0xfff8
	v_lshrrev_b32_e32 v4, 2, v0
	v_lshlrev_b32_e32 v5, 1, v0
	s_sub_i32 s5, s5, s7
	v_and_b32_e32 v4, 4, v4
	v_and_b32_e32 v5, 24, v5
	s_sext_i32_i16 s5, s5
	v_or3_b32 v3, v3, v4, v5
	v_mul_i32_i24_e32 v5, 64, v12
	s_lshr_b32 s4, s4, 3
	s_add_i32 s20, s6, s5
	v_sub_u32_e32 v1, v1, v5
	s_ashr_i32 s21, s20, 31
	s_bfe_i64 s[10:11], s[4:5], 0x100000
	v_lshlrev_b32_e32 v4, 5, v13
	v_ashrrev_i16_sdwa v1, v2, sext(v1) dst_sel:DWORD dst_unused:UNUSED_PAD src0_sel:DWORD src1_sel:BYTE_0
	s_lshl_b64 s[6:7], s[20:21], 20
	s_lshl_b64 s[10:11], s[10:11], 20
	v_and_b32_e32 v4, 32, v4
	v_bfe_i32 v14, v1, 0, 16
	s_add_u32 s58, s54, s10
	v_add_lshl_u32 v1, v4, v14, 1
	s_addc_u32 s59, s55, s11
	s_add_i32 s21, s24, 0
	v_lshl_add_u32 v140, v3, 12, v1
	s_add_i32 m0, s21, 0x10000
	v_lshl_add_u32 v142, v0, 12, v1
	global_load_lds_dwordx4 v140, s[58:59]
	s_add_i32 m0, s21, 0x12000
	s_add_u32 s36, s38, s6
	global_load_lds_dwordx4 v136, s[58:59]
	s_addc_u32 s37, s39, s7
	s_mov_b32 m0, s21
	s_add_i32 s28, s21, 0x2000
	global_load_lds_dwordx4 v142, s[36:37]
	s_mov_b32 m0, s28
	s_add_u32 s6, s58, 0x80000
	global_load_lds_dwordx4 v138, s[36:37]
	s_addc_u32 s7, s59, 0
	s_add_i32 m0, s21, 0x14000
	v_mov_b32_e32 v141, 0
	global_load_lds_dwordx4 v140, s[6:7]
	s_add_i32 m0, s21, 0x16000
	v_mov_b32_e32 v137, v141
	global_load_lds_dwordx4 v136, s[6:7]
	s_add_u32 s6, s36, 0x80000
	s_addc_u32 s7, s37, 0
	s_add_i32 s29, s21, 0x4000
	s_mov_b32 m0, s29
	s_add_i32 s33, s21, 0x6000
	global_load_lds_dwordx4 v142, s[6:7]
	s_mov_b32 m0, s33
	v_mov_b32_e32 v143, v141
	global_load_lds_dwordx4 v138, s[6:7]
	v_mov_b32_e32 v139, v141
	s_mov_b32 s40, 0
	v_lshl_add_u64 v[6:7], s[58:59], 0, v[140:141]
	v_lshl_add_u64 v[4:5], s[58:59], 0, v[136:137]
	v_lshl_add_u64 v[2:3], s[36:37], 0, v[142:143]
	s_cmp_lg_u32 s0, 1
	v_lshl_add_u64 v[0:1], s[36:37], 0, v[138:139]
	s_cbranch_scc1 .LBB0_1230
	s_barrier

.LBB0_1290:
	s_or_b64 exec, exec, s[4:5]
.LBB0_1291:
	s_or_b64 exec, exec, s[10:11]

.LBB0_1370:
	s_or_b64 exec, exec, s[4:5]
.LBB0_1371:
	s_or_b64 exec, exec, s[6:7]
	v_mov_b32_e32 v32, v254
	s_waitcnt lgkmcnt(0)
	v_mov_b64_e32 v[0:1], s[40:41]
	s_barrier
	flat_load_dwordx2 v[0:1], v[0:1] offset:328 sc0 sc1
	s_waitcnt vmcnt(0)
	s_movk_i32 s0, 0x800
	v_cmp_gt_i32_e32 vcc, s0, v32
	s_waitcnt lgkmcnt(0)
	v_readfirstlane_b32 s23, v1
	v_readfirstlane_b32 s24, v0
	s_and_saveexec_b64 s[0:1], vcc
	s_cbranch_execz .LBB0_1374
	v_ashrrev_i32_e32 v33, 31, v32
	v_lshl_add_u64 v[0:1], v[32:33], 3, s[26:27]
	s_mov_b64 s[4:5], 0x50000
	v_lshl_add_u32 v3, v32, 3, 0
	v_add_u32_e32 v2, 0xfffffe00, v32
	v_lshl_add_u64 v[0:1], v[0:1], 0, s[4:5]
	v_add_u32_e32 v3, 0x20000, v3
	s_mov_b64 s[4:5], 0
	s_mov_b64 s[6:7], 0x1000
	s_movk_i32 s8, 0x5ff

.LBB0_1464:
	s_or_b64 exec, exec, s[4:5]
.LBB0_1465:
	s_or_b64 exec, exec, s[10:11]

.LBB0_1520:
	s_or_b64 exec, exec, s[4:5]
.LBB0_1521:
	s_or_b64 exec, exec, s[6:7]
	s_waitcnt lgkmcnt(0)
	v_mov_b32_e32 v0, v254
	s_barrier
	v_readlane_b32 s0, v255, 7
	v_mov_b64_e32 v[0:1], s[58:59]
	flat_load_dwordx2 v[0:1], v[0:1] offset:344 sc0 sc1
	s_waitcnt vmcnt(0)
	v_mov_b32_e32 v8, v254
	v_readlane_b32 s1, v255, 8
	s_and_b64 vcc, exec, s[0:1]
	s_waitcnt lgkmcnt(0)
	v_readfirstlane_b32 s11, v1
	v_readfirstlane_b32 s23, v8
	v_readfirstlane_b32 s10, v0
	s_cbranch_vccz .LBB0_1545
	v_lshlrev_b32_e32 v0, 4, v8
	v_add_u32_e32 v1, 0x2000, v0
	v_ashrrev_i32_e32 v2, 31, v1
	v_lshrrev_b32_e32 v2, 22, v2
	v_add_u32_e32 v2, v1, v2
	v_ashrrev_i32_e32 v9, 10, v2
	v_mul_i32_i24_e32 v2, 0x400, v9
	v_sub_u32_e32 v1, v1, v2
	v_lshrrev_b32_e32 v2, 4, v1
	v_bitop3_b32 v1, v2, v1, 32 bitop3:0x6c
	v_ashrrev_i32_e32 v2, 31, v1
	s_lshr_b32 s4, s3, 29
	v_lshrrev_b32_e32 v2, 26, v2
	s_add_i32 s4, s2, s4
	v_add_u32_e32 v2, v1, v2
	s_and_b32 s5, s4, -8
	s_ashr_i32 s1, s23, 6
	v_ashrrev_i32_e32 v10, 6, v2
	v_and_b32_e32 v2, 0xc0, v2
	s_sub_i32 s5, s2, s5
	s_ashr_i32 s0, s23, 8
	s_lshl_b32 s24, s1, 10
	v_sub_u32_e32 v1, v1, v2
	v_mov_b32_e32 v2, 1
	s_lshl_b32 s7, s5, 5
	s_ashr_i32 s4, s4, 3
	v_ashrrev_i16_sdwa v1, v2, sext(v1) dst_sel:DWORD dst_unused:UNUSED_PAD src0_sel:DWORD src1_sel:BYTE_0
	s_mul_i32 s6, s5, 33
	s_cmp_lt_i32 s5, 0
	v_bfe_i32 v12, v1, 0, 16
	v_bfe_i32 v1, v8, 27, 1
	s_cselect_b32 s5, s6, s7
	v_lshrrev_b32_e32 v1, 22, v1
	s_add_i32 s4, s5, s4
	v_add_u32_e32 v1, v0, v1
	s_ashr_i32 s5, s4, 31
	v_and_b32_e32 v1, 0xfffffc00, v1
	s_lshr_b32 s5, s5, 26
	v_sub_u32_e32 v0, v0, v1
	s_add_i32 s5, s4, s5
	v_lshrrev_b32_e32 v1, 4, v0
	s_ashr_i32 s6, s5, 6
	s_andn2_b32 s5, s5, 63
	v_bitop3_b32 v1, v1, v0, 32 bitop3:0x6c
	v_ashrrev_i32_e32 v0, 31, v0
	s_sub_i32 s5, s4, s5
	v_lshrrev_b32_e32 v0, 26, v0
	s_bfe_i32 s4, s5, 0x80000
	v_add_u32_e32 v0, v1, v0
	s_bfe_u32 s4, s4, 0x3000c
	v_lshlrev_b32_e32 v3, 3, v9
	v_ashrrev_i32_e32 v13, 6, v0
	v_ashrrev_i32_e32 v0, 31, v8
	s_add_i32 s7, s5, s4
	v_and_b32_e32 v3, 0xffff0, v3
	v_lshlrev_b32_e32 v4, 5, v9
	v_lshrrev_b32_e32 v0, 26, v0
	s_bfe_i32 s4, s7, 0x80000
	s_and_b32 s7, s7, 0xf8
	v_add_u32_e32 v3, v10, v3
	v_and_b32_e32 v11, 32, v4
	v_add_u32_e32 v0, v8, v0
	s_sub_i32 s5, s5, s7
	v_lshl_or_b32 v3, v3, 11, v11
	v_ashrrev_i32_e32 v14, 6, v0
	s_lshl_b32 s6, s6, 3
	s_sext_i32_i16 s4, s4
	s_sext_i32_i8 s5, s5
	v_add_lshl_u32 v138, v3, v12, 1
	v_lshlrev_b32_e32 v3, 5, v14
	s_lshr_b32 s4, s4, 3
	s_add_i32 s66, s6, s5
	v_lshlrev_b32_e32 v0, 3, v14
	v_and_b32_e32 v15, 32, v3
	v_mul_i32_i24_e32 v3, 64, v13
	s_ashr_i32 s67, s66, 31
	s_bfe_i64 s[8:9], s[4:5], 0x100000
	v_and_b32_e32 v0, 0xffff0, v0
	v_sub_u32_e32 v1, v1, v3
	s_lshl_b64 s[6:7], s[66:67], 20
	s_lshl_b64 s[8:9], s[8:9], 20
	v_readlane_b32 s12, v255, 26
	v_add_u32_e32 v0, v13, v0
	v_ashrrev_i16_sdwa v1, v2, sext(v1) dst_sel:DWORD dst_unused:UNUSED_PAD src0_sel:DWORD src1_sel:BYTE_0
	v_readlane_b32 s13, v255, 27
	s_add_u32 s68, s12, s8
	v_lshl_or_b32 v0, v0, 11, v15
	v_bfe_i32 v16, v1, 0, 16
	s_addc_u32 s69, s13, s9
	s_add_i32 s25, s24, 0
	v_add_lshl_u32 v140, v0, v16, 1
	s_add_i32 m0, s25, 0x10000
	s_load_dwordx2 s[12:13], s[88:89], 0x168
	global_load_lds_dwordx4 v140, s[68:69]
	s_add_i32 m0, s25, 0x12000
	s_add_u32 s8, s38, s6
	global_load_lds_dwordx4 v138, s[68:69]
	s_addc_u32 s9, s39, s7
	s_mov_b32 m0, s25
	s_add_i32 s28, s25, 0x2000
	global_load_lds_dwordx4 v140, s[8:9]
	s_mov_b32 m0, s28
	s_add_u32 s6, s68, 0x80000
	global_load_lds_dwordx4 v138, s[8:9]
	s_addc_u32 s7, s69, 0
	s_add_i32 m0, s25, 0x14000
	v_mov_b32_e32 v141, 0
	global_load_lds_dwordx4 v140, s[6:7]
	s_add_i32 m0, s25, 0x16000
	v_mov_b32_e32 v139, v141
	global_load_lds_dwordx4 v138, s[6:7]
	s_add_u32 s6, s8, 0x80000
	s_addc_u32 s7, s9, 0
	s_add_i32 s29, s25, 0x4000
	s_mov_b32 m0, s29
	s_add_i32 s33, s25, 0x6000
	global_load_lds_dwordx4 v140, s[6:7]
	s_mov_b32 m0, s33
	s_mov_b32 s36, 0
	global_load_lds_dwordx4 v138, s[6:7]
	v_lshl_add_u64 v[6:7], s[68:69], 0, v[140:141]
	v_lshl_add_u64 v[4:5], s[68:69], 0, v[138:139]
	v_lshl_add_u64 v[2:3], s[8:9], 0, v[140:141]
	s_cmp_lg_u32 s0, 1
	v_lshl_add_u64 v[0:1], s[8:9], 0, v[138:139]
	s_cbranch_scc1 .LBB0_1524
	s_barrier

.LBB0_1596:
	s_or_b64 exec, exec, s[4:5]
.LBB0_1597:
	s_or_b64 exec, exec, s[10:11]

.LBB0_1668:
	s_or_b64 exec, exec, s[4:5]
.LBB0_1669:
	s_or_b64 exec, exec, s[6:7]
	s_waitcnt lgkmcnt(0)
	v_mov_b32_e32 v0, v254
	v_mov_b32_e32 v9, v254
	s_barrier
	s_and_b64 vcc, exec, s[56:57]
	v_readfirstlane_b32 s23, v9
	s_cbranch_vccz .LBB0_1681
	v_lshlrev_b32_e32 v0, 4, v9
	v_add_u32_e32 v1, 0x2000, v0
	v_ashrrev_i32_e32 v2, 31, v1
	v_lshrrev_b32_e32 v2, 22, v2
	v_add_u32_e32 v2, v1, v2
	v_ashrrev_i32_e32 v8, 10, v2
	v_mul_i32_i24_e32 v2, 0x400, v8
	v_sub_u32_e32 v1, v1, v2
	v_lshrrev_b32_e32 v2, 4, v1
	v_bitop3_b32 v1, v2, v1, 32 bitop3:0x6c
	v_ashrrev_i32_e32 v2, 31, v1
	v_lshrrev_b32_e32 v2, 26, v2
	v_add_u32_e32 v2, v1, v2
	v_lshlrev_b32_e32 v3, 3, v8
	v_ashrrev_i32_e32 v10, 6, v2
	v_and_b32_e32 v3, -16, v3
	v_add_u32_e32 v3, v10, v3
	v_and_b32_e32 v4, 3, v10
	s_mov_b32 s4, 0xfffe0
	v_lshrrev_b32_e32 v5, 2, v3
	v_lshlrev_b32_e32 v6, 1, v3
	v_and_b32_e32 v2, 0xc0, v2
	v_and_or_b32 v4, v3, s4, v4
	v_and_b32_e32 v5, 4, v5
	v_and_b32_e32 v6, 24, v6
	v_sub_u32_e32 v1, v1, v2
	v_mov_b32_e32 v2, 1
	v_or3_b32 v4, v4, v5, v6
	v_lshlrev_b32_e32 v5, 5, v8
	v_ashrrev_i16_sdwa v1, v2, sext(v1) dst_sel:DWORD dst_unused:UNUSED_PAD src0_sel:DWORD src1_sel:BYTE_0
	v_and_b32_e32 v5, 32, v5
	v_bfe_i32 v11, v1, 0, 16
	v_add_lshl_u32 v1, v5, v11, 1
	v_lshl_add_u32 v128, v4, 12, v1
	v_lshl_add_u32 v130, v3, 12, v1
	v_bfe_i32 v1, v9, 27, 1
	v_lshrrev_b32_e32 v1, 22, v1
	v_add_u32_e32 v1, v0, v1
	v_and_b32_e32 v1, 0xfffffc00, v1
	v_sub_u32_e32 v0, v0, v1
	v_lshrrev_b32_e32 v1, 4, v0
	v_bitop3_b32 v1, v1, v0, 32 bitop3:0x6c
	v_ashrrev_i32_e32 v0, 31, v0
	v_lshrrev_b32_e32 v0, 26, v0
	v_add_u32_e32 v0, v1, v0
	v_ashrrev_i32_e32 v12, 6, v0
	v_ashrrev_i32_e32 v0, 31, v9
	v_lshrrev_b32_e32 v0, 26, v0
	v_add_u32_e32 v0, v9, v0
	v_ashrrev_i32_e32 v13, 6, v0
	v_lshlrev_b32_e32 v0, 3, v13
	v_and_b32_e32 v0, -16, v0
	v_add_u32_e32 v0, v12, v0
	v_and_b32_e32 v3, 3, v12
	v_and_or_b32 v3, v0, s4, v3
	s_lshr_b32 s4, s3, 29
	s_add_i32 s4, s2, s4
	s_ashr_i32 s1, s23, 6
	s_ashr_i32 s5, s4, 3
	s_and_b32 s4, s4, -8
	s_ashr_i32 s0, s23, 8
	s_lshl_b32 s24, s1, 10
	s_sub_i32 s4, s2, s4
	s_cmp_lt_i32 s4, 0
	s_movk_i32 s25, 0xb1
	s_cselect_b32 s6, s25, 0xb0
	s_mul_i32 s4, s4, s6
	s_add_i32 s4, s4, s5
	s_mul_hi_i32 s5, s4, 0x2e8ba2e9
	s_lshr_b32 s6, s5, 31
	s_ashr_i32 s5, s5, 6
	s_add_i32 s5, s5, s6
	s_lshl_b32 s6, s5, 3
	s_mulk_i32 s5, 0x160
	s_sub_i32 s5, s4, s5
	s_sext_i32_i16 s4, s5
	s_bfe_u32 s4, s4, 0x3001c
	s_add_i32 s7, s5, s4
	s_sext_i32_i16 s4, s7
	s_and_b32 s7, s7, 0xfff8
	v_lshrrev_b32_e32 v4, 2, v0
	v_lshlrev_b32_e32 v5, 1, v0
	s_sub_i32 s5, s5, s7
	v_and_b32_e32 v4, 4, v4
	v_and_b32_e32 v5, 24, v5
	s_sext_i32_i16 s5, s5
	v_or3_b32 v3, v3, v4, v5
	v_mul_i32_i24_e32 v5, 64, v12
	s_lshr_b32 s4, s4, 3
	s_add_i32 s18, s6, s5
	v_sub_u32_e32 v1, v1, v5
	s_ashr_i32 s19, s18, 31
	s_bfe_i64 s[8:9], s[4:5], 0x100000
	v_lshlrev_b32_e32 v4, 5, v13
	v_ashrrev_i16_sdwa v1, v2, sext(v1) dst_sel:DWORD dst_unused:UNUSED_PAD src0_sel:DWORD src1_sel:BYTE_0
	s_lshl_b64 s[6:7], s[18:19], 20
	s_lshl_b64 s[8:9], s[8:9], 20
	v_readlane_b32 s56, v255, 24
	v_and_b32_e32 v4, 32, v4
	v_bfe_i32 v14, v1, 0, 16
	v_readlane_b32 s57, v255, 25
	s_add_u32 s44, s56, s8
	v_add_lshl_u32 v1, v4, v14, 1
	s_addc_u32 s45, s57, s9
	s_add_i32 s19, s24, 0
	v_lshl_add_u32 v132, v3, 12, v1
	s_add_i32 m0, s19, 0x10000
	v_lshl_add_u32 v134, v0, 12, v1
	global_load_lds_dwordx4 v132, s[44:45]
	s_add_i32 m0, s19, 0x12000
	s_add_u32 s20, s38, s6
	global_load_lds_dwordx4 v128, s[44:45]
	s_addc_u32 s21, s39, s7
	s_mov_b32 m0, s19
	s_add_i32 s28, s19, 0x2000
	global_load_lds_dwordx4 v134, s[20:21]
	s_mov_b32 m0, s28
	s_add_u32 s6, s44, 0x80000
	global_load_lds_dwordx4 v130, s[20:21]
	s_addc_u32 s7, s45, 0
	s_add_i32 m0, s19, 0x14000
	v_mov_b32_e32 v133, 0
	global_load_lds_dwordx4 v132, s[6:7]
	s_add_i32 m0, s19, 0x16000
	v_mov_b32_e32 v129, v133
	global_load_lds_dwordx4 v128, s[6:7]
	s_add_u32 s6, s20, 0x80000
	s_addc_u32 s7, s21, 0
	s_add_i32 s29, s19, 0x4000
	s_mov_b32 m0, s29
	s_add_i32 s33, s19, 0x6000
	global_load_lds_dwordx4 v134, s[6:7]
	s_mov_b32 m0, s33
	v_mov_b32_e32 v135, v133
	global_load_lds_dwordx4 v130, s[6:7]
	v_mov_b32_e32 v131, v133
	s_mov_b32 s36, 0
	v_lshl_add_u64 v[6:7], s[44:45], 0, v[132:133]
	v_lshl_add_u64 v[4:5], s[44:45], 0, v[128:129]
	v_lshl_add_u64 v[2:3], s[20:21], 0, v[134:135]
	s_cmp_lg_u32 s0, 1
	v_lshl_add_u64 v[0:1], s[20:21], 0, v[130:131]
	s_cbranch_scc1 .LBB0_1672
	s_barrier

.LBB0_1732:
	s_or_b64 exec, exec, s[4:5]
.LBB0_1733:
	s_or_b64 exec, exec, s[10:11]

.LBB0_1805:
	s_or_b64 exec, exec, s[8:9]
.LBB0_1806:
	s_or_b64 exec, exec, s[6:7]
